# GEMM tile-loop headers: removed the compiler's s_waitcnt vmcnt(0) (full store drain at every tile start; no load is outstanding there any more) - the counted waits absorb it
# speedup vs baseline: 1.0020x; 1.0020x over previous
; template <class Epi, class Sched, bool ALIGN_EPI = false, bool SP2 = false>
; __device__ __forceinline__ void gemm_phase(PG8_LAS unsigned char* lds, const Gemm g, const Sched& S, const Epi& E) {
;     ...
;     for (;;) {
;         const bool has_next = S.next(ui + 1, nxt);
;         const char* nA = has_next ? (const char*)g.A + (size_t)nxt.pm * tstep : cA; const char* nB = has_next ? (const char*)g.Bt + (size_t)nxt.pn * tstep : cB;
;         for (int t = 0; t < nt; t += 2) {
;             const bool last = (t == nt - 2);
;             const char* a1 = cA + (size_t)(t + 1) * kstep;
;             const char* a2 = last ? nA : cA + (size_t)(t + 2) * kstep; const char* b2 = last ? nB : cB + (size_t)(t + 2) * kstep;
;             const char* a3 = a2 + kstep; const char* b3 = b2 + kstep;
;     ...
; #pragma unroll
;         for (int a = 0; a < 2; ++a)
; #pragma unroll
;             for (int b = 0; b < 2; ++b)
; #pragma unroll
;                 for (int m = 0; m < 4; ++m)
; #pragma unroll
;                     for (int n = 0; n < 2; ++n) acc[a][b][m][n] = (f32x4){0.f, 0.f, 0.f, 0.f};
;         cur = nxt; cA = nA; cB = nB; ++ui;
.LBB0_1246:
	s_ashr_i32 s29, s28, 31
	s_lshl_b64 s[8:9], s[28:29], 19
	s_add_u32 s30, s92, s8
	s_addc_u32 s31, s93, s9
	s_and_b64 s[8:9], s[2:3], exec
	s_cselect_b32 s10, s31, s5
	s_cselect_b32 s11, s30, s4
	s_ashr_i32 s27, s26, 31
	s_lshl_b64 s[8:9], s[26:27], 19
	s_add_u32 s34, s37, s8
	s_addc_u32 s35, s38, s9
	s_and_b64 s[8:9], s[2:3], exec
	s_cselect_b32 s27, s35, s7
	s_cselect_b32 s29, s34, s6
	s_add_u32 s4, s4, 0x40080
	s_addc_u32 s5, s5, 0
	s_add_u32 s52, s6, 0x100
	v_mov_b32_e32 v0, 0
	s_addc_u32 s53, s7, 0
	s_mov_b32 s56, -2
	v_mov_b32_e32 v1, v0
	v_mov_b32_e32 v2, v0
	v_mov_b32_e32 v3, v0
	v_mov_b32_e32 v4, v0
	v_mov_b32_e32 v5, v0
	v_mov_b32_e32 v6, v0
	v_mov_b32_e32 v7, v0
	v_mov_b32_e32 v16, v0
	v_mov_b32_e32 v17, v0
	v_mov_b32_e32 v18, v0
	v_mov_b32_e32 v19, v0
	v_mov_b32_e32 v20, v0
	v_mov_b32_e32 v21, v0
	v_mov_b32_e32 v22, v0
	v_mov_b32_e32 v23, v0
	v_mov_b32_e32 v32, v0
	v_mov_b32_e32 v33, v0
	v_mov_b32_e32 v34, v0
	v_mov_b32_e32 v35, v0
	s_nop 0
	v_mov_b32_e32 v36, v0
	v_mov_b32_e32 v37, v0
	v_mov_b32_e32 v38, v0
	v_mov_b32_e32 v39, v0
	v_mov_b32_e32 v48, v0
	v_mov_b32_e32 v49, v0
	v_mov_b32_e32 v50, v0
	v_mov_b32_e32 v51, v0
	v_mov_b32_e32 v52, v0
	v_mov_b32_e32 v53, v0
	v_mov_b32_e32 v54, v0
	v_mov_b32_e32 v55, v0
	v_mov_b32_e32 v8, v0
	v_mov_b32_e32 v9, v0
	v_mov_b32_e32 v10, v0
	v_mov_b32_e32 v11, v0
	v_mov_b32_e32 v12, v0
	v_mov_b32_e32 v13, v0
	v_mov_b32_e32 v14, v0
	v_mov_b32_e32 v15, v0
	v_mov_b32_e32 v24, v0
	v_mov_b32_e32 v25, v0
	v_mov_b32_e32 v26, v0
	v_mov_b32_e32 v27, v0
	v_mov_b32_e32 v28, v0
	v_mov_b32_e32 v29, v0
	v_mov_b32_e32 v30, v0
	v_mov_b32_e32 v31, v0
	v_mov_b32_e32 v40, v0
	v_mov_b32_e32 v41, v0
	v_mov_b32_e32 v42, v0
	v_mov_b32_e32 v43, v0
	v_mov_b32_e32 v44, v0
	v_mov_b32_e32 v45, v0
	v_mov_b32_e32 v46, v0
	v_mov_b32_e32 v47, v0
	v_mov_b32_e32 v56, v0
	v_mov_b32_e32 v57, v0
	v_mov_b32_e32 v58, v0
	v_mov_b32_e32 v59, v0
	v_mov_b32_e32 v60, v0
	v_mov_b32_e32 v61, v0
	v_mov_b32_e32 v62, v0
	v_mov_b32_e32 v63, v0
	v_mov_b32_e32 v64, v0
	v_mov_b32_e32 v65, v0
	v_mov_b32_e32 v66, v0
	v_mov_b32_e32 v67, v0
	v_mov_b32_e32 v68, v0
	v_mov_b32_e32 v69, v0
	v_mov_b32_e32 v70, v0
	v_mov_b32_e32 v71, v0
	v_mov_b32_e32 v80, v0
	v_mov_b32_e32 v81, v0
	v_mov_b32_e32 v82, v0
	v_mov_b32_e32 v83, v0
	v_mov_b32_e32 v84, v0
	v_mov_b32_e32 v85, v0
	v_mov_b32_e32 v86, v0
	v_mov_b32_e32 v87, v0
	v_mov_b32_e32 v96, v0
	v_mov_b32_e32 v97, v0
	v_mov_b32_e32 v98, v0
	v_mov_b32_e32 v99, v0
	v_mov_b32_e32 v100, v0
	v_mov_b32_e32 v101, v0
	v_mov_b32_e32 v102, v0
	v_mov_b32_e32 v103, v0
	v_mov_b32_e32 v112, v0
	v_mov_b32_e32 v113, v0
	v_mov_b32_e32 v114, v0
	v_mov_b32_e32 v115, v0
	v_mov_b32_e32 v116, v0
	v_mov_b32_e32 v117, v0
	v_mov_b32_e32 v118, v0
	v_mov_b32_e32 v119, v0
	v_mov_b32_e32 v72, v0
	v_mov_b32_e32 v73, v0
	v_mov_b32_e32 v74, v0
	v_mov_b32_e32 v75, v0
	v_mov_b32_e32 v76, v0
	v_mov_b32_e32 v77, v0
	v_mov_b32_e32 v78, v0
	v_mov_b32_e32 v79, v0
	v_mov_b32_e32 v88, v0
	v_mov_b32_e32 v89, v0
	v_mov_b32_e32 v90, v0
	v_mov_b32_e32 v91, v0
	v_mov_b32_e32 v92, v0
	v_mov_b32_e32 v93, v0
	v_mov_b32_e32 v94, v0
	v_mov_b32_e32 v95, v0
	v_mov_b32_e32 v104, v0
	v_mov_b32_e32 v105, v0
	v_mov_b32_e32 v106, v0
	v_mov_b32_e32 v107, v0
	v_mov_b32_e32 v108, v0
	v_mov_b32_e32 v109, v0
	v_mov_b32_e32 v110, v0
	v_mov_b32_e32 v111, v0
	v_mov_b32_e32 v120, v0
	v_mov_b32_e32 v121, v0
	v_mov_b32_e32 v122, v0
	v_mov_b32_e32 v123, v0
	v_mov_b32_e32 v124, v0
	v_mov_b32_e32 v125, v0
	v_mov_b32_e32 v126, v0
	v_mov_b32_e32 v127, v0

; template <class Epi, class Sched, bool ALIGN_EPI = false, bool SP2 = false>
; __device__ __forceinline__ void gemm_phase(PG8_LAS unsigned char* lds, const Gemm g, const Sched& S, const Epi& E) {
;     ...
;     for (;;) {
;         const bool has_next = S.next(ui + 1, nxt);
;         const char* nA = has_next ? (const char*)g.A + (size_t)nxt.pm * tstep : cA; const char* nB = has_next ? (const char*)g.Bt + (size_t)nxt.pn * tstep : cB;
;         for (int t = 0; t < nt; t += 2) {
;             const bool last = (t == nt - 2);
;             const char* a1 = cA + (size_t)(t + 1) * kstep;
;             const char* a2 = last ? nA : cA + (size_t)(t + 2) * kstep; const char* b2 = last ? nB : cB + (size_t)(t + 2) * kstep;
;             const char* a3 = a2 + kstep; const char* b3 = b2 + kstep;
;     ...
; #pragma unroll
;         for (int a = 0; a < 2; ++a)
; #pragma unroll
;             for (int b = 0; b < 2; ++b)
; #pragma unroll
;                 for (int m = 0; m < 4; ++m)
; #pragma unroll
;                     for (int n = 0; n < 2; ++n) acc[a][b][m][n] = (f32x4){0.f, 0.f, 0.f, 0.f};
;         cur = nxt; cA = nA; cB = nB; ++ui;
.LBB0_1270:
	s_ashr_i32 s21, s20, 31
	s_lshl_b64 s[22:23], s[20:21], 18
	s_add_u32 s22, s48, s22
	s_addc_u32 s23, s49, s23
	s_and_b64 s[24:25], s[4:5], exec
	s_cselect_b32 s21, s23, s29
	s_cselect_b32 s56, s22, s28
	s_ashr_i32 s19, s18, 31
	s_lshl_b64 s[24:25], s[18:19], 18
	s_add_u32 s24, s78, s24
	s_addc_u32 s25, s79, s25
	s_and_b64 s[34:35], s[4:5], exec
	s_cselect_b32 s19, s25, s31
	s_cselect_b32 s57, s24, s30
	s_add_u32 s28, s28, 0x20080
	s_addc_u32 s29, s29, 0
	s_add_u32 s61, s30, 0x100
	v_mov_b32_e32 v0, 0
	s_addc_u32 s62, s31, 0
	s_mov_b32 s63, -2
	v_mov_b32_e32 v1, v0
	v_mov_b32_e32 v2, v0
	v_mov_b32_e32 v3, v0
	v_mov_b32_e32 v4, v0
	v_mov_b32_e32 v5, v0
	v_mov_b32_e32 v6, v0
	v_mov_b32_e32 v7, v0
	v_mov_b32_e32 v16, v0
	v_mov_b32_e32 v17, v0
	v_mov_b32_e32 v18, v0
	v_mov_b32_e32 v19, v0
	v_mov_b32_e32 v20, v0
	v_mov_b32_e32 v21, v0
	v_mov_b32_e32 v22, v0
	v_mov_b32_e32 v23, v0
	v_mov_b32_e32 v32, v0
	v_mov_b32_e32 v33, v0
	v_mov_b32_e32 v34, v0
	v_mov_b32_e32 v35, v0
	s_nop 0
	v_mov_b32_e32 v36, v0
	v_mov_b32_e32 v37, v0
	v_mov_b32_e32 v38, v0
	v_mov_b32_e32 v39, v0
	v_mov_b32_e32 v48, v0
	v_mov_b32_e32 v49, v0
	v_mov_b32_e32 v50, v0
	v_mov_b32_e32 v51, v0
	v_mov_b32_e32 v52, v0
	v_mov_b32_e32 v53, v0
	v_mov_b32_e32 v54, v0
	v_mov_b32_e32 v55, v0
	v_mov_b32_e32 v8, v0
	v_mov_b32_e32 v9, v0
	v_mov_b32_e32 v10, v0
	v_mov_b32_e32 v11, v0
	v_mov_b32_e32 v12, v0
	v_mov_b32_e32 v13, v0
	v_mov_b32_e32 v14, v0
	v_mov_b32_e32 v15, v0
	v_mov_b32_e32 v24, v0
	v_mov_b32_e32 v25, v0
	v_mov_b32_e32 v26, v0
	v_mov_b32_e32 v27, v0
	v_mov_b32_e32 v28, v0
	v_mov_b32_e32 v29, v0
	v_mov_b32_e32 v30, v0
	v_mov_b32_e32 v31, v0
	v_mov_b32_e32 v40, v0
	v_mov_b32_e32 v41, v0
	v_mov_b32_e32 v42, v0
	v_mov_b32_e32 v43, v0
	v_mov_b32_e32 v44, v0
	v_mov_b32_e32 v45, v0
	v_mov_b32_e32 v46, v0
	v_mov_b32_e32 v47, v0
	v_mov_b32_e32 v56, v0
	v_mov_b32_e32 v57, v0
	v_mov_b32_e32 v58, v0
	v_mov_b32_e32 v59, v0
	v_mov_b32_e32 v60, v0
	v_mov_b32_e32 v61, v0
	v_mov_b32_e32 v62, v0
	v_mov_b32_e32 v63, v0
	v_mov_b32_e32 v64, v0
	v_mov_b32_e32 v65, v0
	v_mov_b32_e32 v66, v0
	v_mov_b32_e32 v67, v0
	v_mov_b32_e32 v68, v0
	v_mov_b32_e32 v69, v0
	v_mov_b32_e32 v70, v0
	v_mov_b32_e32 v71, v0
	v_mov_b32_e32 v80, v0
	v_mov_b32_e32 v81, v0
	v_mov_b32_e32 v82, v0
	v_mov_b32_e32 v83, v0
	v_mov_b32_e32 v84, v0
	v_mov_b32_e32 v85, v0
	v_mov_b32_e32 v86, v0
	v_mov_b32_e32 v87, v0
	v_mov_b32_e32 v96, v0
	v_mov_b32_e32 v97, v0
	v_mov_b32_e32 v98, v0
	v_mov_b32_e32 v99, v0
	v_mov_b32_e32 v100, v0
	v_mov_b32_e32 v101, v0
	v_mov_b32_e32 v102, v0
	v_mov_b32_e32 v103, v0
	v_mov_b32_e32 v112, v0
	v_mov_b32_e32 v113, v0
	v_mov_b32_e32 v114, v0
	v_mov_b32_e32 v115, v0
	v_mov_b32_e32 v116, v0
	v_mov_b32_e32 v117, v0
	v_mov_b32_e32 v118, v0
	v_mov_b32_e32 v119, v0
	v_mov_b32_e32 v72, v0
	v_mov_b32_e32 v73, v0
	v_mov_b32_e32 v74, v0
	v_mov_b32_e32 v75, v0
	v_mov_b32_e32 v76, v0
	v_mov_b32_e32 v77, v0
	v_mov_b32_e32 v78, v0
	v_mov_b32_e32 v79, v0
	v_mov_b32_e32 v88, v0
	v_mov_b32_e32 v89, v0
	v_mov_b32_e32 v90, v0
	v_mov_b32_e32 v91, v0
	v_mov_b32_e32 v92, v0
	v_mov_b32_e32 v93, v0
	v_mov_b32_e32 v94, v0
	v_mov_b32_e32 v95, v0
	v_mov_b32_e32 v104, v0
	v_mov_b32_e32 v105, v0
	v_mov_b32_e32 v106, v0
	v_mov_b32_e32 v107, v0
	v_mov_b32_e32 v108, v0
	v_mov_b32_e32 v109, v0
	v_mov_b32_e32 v110, v0
	v_mov_b32_e32 v111, v0
	v_mov_b32_e32 v120, v0
	v_mov_b32_e32 v121, v0
	v_mov_b32_e32 v122, v0
	v_mov_b32_e32 v123, v0
	v_mov_b32_e32 v124, v0
	v_mov_b32_e32 v125, v0
	v_mov_b32_e32 v126, v0
	v_mov_b32_e32 v127, v0

; template <class Epi, class Sched, bool ALIGN_EPI = false, bool SP2 = false>
; __device__ __forceinline__ void gemm_phase(PG8_LAS unsigned char* lds, const Gemm g, const Sched& S, const Epi& E) {
;     ...
;     for (;;) {
;         const bool has_next = S.next(ui + 1, nxt);
;         const char* nA = has_next ? (const char*)g.A + (size_t)nxt.pm * tstep : cA; const char* nB = has_next ? (const char*)g.Bt + (size_t)nxt.pn * tstep : cB;
;         for (int t = 0; t < nt; t += 2) {
;             const bool last = (t == nt - 2);
;             const char* a1 = cA + (size_t)(t + 1) * kstep;
;             const char* a2 = last ? nA : cA + (size_t)(t + 2) * kstep; const char* b2 = last ? nB : cB + (size_t)(t + 2) * kstep;
;             const char* a3 = a2 + kstep; const char* b3 = b2 + kstep;
;     ...
; #pragma unroll
;         for (int a = 0; a < 2; ++a)
; #pragma unroll
;             for (int b = 0; b < 2; ++b)
; #pragma unroll
;                 for (int m = 0; m < 4; ++m)
; #pragma unroll
;                     for (int n = 0; n < 2; ++n) acc[a][b][m][n] = (f32x4){0.f, 0.f, 0.f, 0.f};
;         cur = nxt; cA = nA; cB = nB; ++ui;
.LBB0_1294:
	s_ashr_i32 s29, s28, 31
	s_lshl_b64 s[10:11], s[28:29], 19
	s_add_u32 s30, s92, s10
	s_addc_u32 s31, s93, s11
	s_and_b64 s[10:11], s[4:5], exec
	s_cselect_b32 s12, s31, s7
	s_cselect_b32 s13, s30, s6
	s_ashr_i32 s27, s26, 31
	s_lshl_b64 s[10:11], s[26:27], 19
	s_add_u32 s34, s37, s10
	s_addc_u32 s35, s38, s11
	s_and_b64 s[10:11], s[4:5], exec
	s_cselect_b32 s27, s35, s9
	s_cselect_b32 s29, s34, s8
	s_add_u32 s6, s6, 0x40080
	s_addc_u32 s7, s7, 0
	s_add_u32 s52, s8, 0x100
	v_mov_b32_e32 v0, 0
	s_addc_u32 s53, s9, 0
	s_mov_b32 s68, -2
	v_mov_b32_e32 v1, v0
	v_mov_b32_e32 v2, v0
	v_mov_b32_e32 v3, v0
	v_mov_b32_e32 v4, v0
	v_mov_b32_e32 v5, v0
	v_mov_b32_e32 v6, v0
	v_mov_b32_e32 v7, v0
	v_mov_b32_e32 v16, v0
	v_mov_b32_e32 v17, v0
	v_mov_b32_e32 v18, v0
	v_mov_b32_e32 v19, v0
	v_mov_b32_e32 v20, v0
	v_mov_b32_e32 v21, v0
	v_mov_b32_e32 v22, v0
	v_mov_b32_e32 v23, v0
	v_mov_b32_e32 v32, v0
	v_mov_b32_e32 v33, v0
	v_mov_b32_e32 v34, v0
	v_mov_b32_e32 v35, v0
	s_nop 0
	v_mov_b32_e32 v36, v0
	v_mov_b32_e32 v37, v0
	v_mov_b32_e32 v38, v0
	v_mov_b32_e32 v39, v0
	v_mov_b32_e32 v48, v0
	v_mov_b32_e32 v49, v0
	v_mov_b32_e32 v50, v0
	v_mov_b32_e32 v51, v0
	v_mov_b32_e32 v52, v0
	v_mov_b32_e32 v53, v0
	v_mov_b32_e32 v54, v0
	v_mov_b32_e32 v55, v0
	v_mov_b32_e32 v8, v0
	v_mov_b32_e32 v9, v0
	v_mov_b32_e32 v10, v0
	v_mov_b32_e32 v11, v0
	v_mov_b32_e32 v12, v0
	v_mov_b32_e32 v13, v0
	v_mov_b32_e32 v14, v0
	v_mov_b32_e32 v15, v0
	v_mov_b32_e32 v24, v0
	v_mov_b32_e32 v25, v0
	v_mov_b32_e32 v26, v0
	v_mov_b32_e32 v27, v0
	v_mov_b32_e32 v28, v0
	v_mov_b32_e32 v29, v0
	v_mov_b32_e32 v30, v0
	v_mov_b32_e32 v31, v0
	v_mov_b32_e32 v40, v0
	v_mov_b32_e32 v41, v0
	v_mov_b32_e32 v42, v0
	v_mov_b32_e32 v43, v0
	v_mov_b32_e32 v44, v0
	v_mov_b32_e32 v45, v0
	v_mov_b32_e32 v46, v0
	v_mov_b32_e32 v47, v0
	v_mov_b32_e32 v56, v0
	v_mov_b32_e32 v57, v0
	v_mov_b32_e32 v58, v0
	v_mov_b32_e32 v59, v0
	v_mov_b32_e32 v60, v0
	v_mov_b32_e32 v61, v0
	v_mov_b32_e32 v62, v0
	v_mov_b32_e32 v63, v0
	v_mov_b32_e32 v64, v0
	v_mov_b32_e32 v65, v0
	v_mov_b32_e32 v66, v0
	v_mov_b32_e32 v67, v0
	v_mov_b32_e32 v68, v0
	v_mov_b32_e32 v69, v0
	v_mov_b32_e32 v70, v0
	v_mov_b32_e32 v71, v0
	v_mov_b32_e32 v80, v0
	v_mov_b32_e32 v81, v0
	v_mov_b32_e32 v82, v0
	v_mov_b32_e32 v83, v0
	v_mov_b32_e32 v84, v0
	v_mov_b32_e32 v85, v0
	v_mov_b32_e32 v86, v0
	v_mov_b32_e32 v87, v0
	v_mov_b32_e32 v96, v0
	v_mov_b32_e32 v97, v0
	v_mov_b32_e32 v98, v0
	v_mov_b32_e32 v99, v0
	v_mov_b32_e32 v100, v0
	v_mov_b32_e32 v101, v0
	v_mov_b32_e32 v102, v0
	v_mov_b32_e32 v103, v0
	v_mov_b32_e32 v112, v0
	v_mov_b32_e32 v113, v0
	v_mov_b32_e32 v114, v0
	v_mov_b32_e32 v115, v0
	v_mov_b32_e32 v116, v0
	v_mov_b32_e32 v117, v0
	v_mov_b32_e32 v118, v0
	v_mov_b32_e32 v119, v0
	v_mov_b32_e32 v72, v0
	v_mov_b32_e32 v73, v0
	v_mov_b32_e32 v74, v0
	v_mov_b32_e32 v75, v0
	v_mov_b32_e32 v76, v0
	v_mov_b32_e32 v77, v0
	v_mov_b32_e32 v78, v0
	v_mov_b32_e32 v79, v0
	v_mov_b32_e32 v88, v0
	v_mov_b32_e32 v89, v0
	v_mov_b32_e32 v90, v0
	v_mov_b32_e32 v91, v0
	v_mov_b32_e32 v92, v0
	v_mov_b32_e32 v93, v0
	v_mov_b32_e32 v94, v0
	v_mov_b32_e32 v95, v0
	v_mov_b32_e32 v104, v0
	v_mov_b32_e32 v105, v0
	v_mov_b32_e32 v106, v0
	v_mov_b32_e32 v107, v0
	v_mov_b32_e32 v108, v0
	v_mov_b32_e32 v109, v0
	v_mov_b32_e32 v110, v0
	v_mov_b32_e32 v111, v0
	v_mov_b32_e32 v120, v0
	v_mov_b32_e32 v121, v0
	v_mov_b32_e32 v122, v0
	v_mov_b32_e32 v123, v0
	v_mov_b32_e32 v124, v0
	v_mov_b32_e32 v125, v0
	v_mov_b32_e32 v126, v0
	v_mov_b32_e32 v127, v0

; template <class Epi, class Sched, bool ALIGN_EPI = false, bool SP2 = false>
; __device__ __forceinline__ void gemm_phase(PG8_LAS unsigned char* lds, const Gemm g, const Sched& S, const Epi& E) {
;     ...
;     for (;;) {
;         const bool has_next = S.next(ui + 1, nxt);
;         const char* nA = has_next ? (const char*)g.A + (size_t)nxt.pm * tstep : cA; const char* nB = has_next ? (const char*)g.Bt + (size_t)nxt.pn * tstep : cB;
;         for (int t = 0; t < nt; t += 2) {
;             const bool last = (t == nt - 2);
;             const char* a1 = cA + (size_t)(t + 1) * kstep;
;             const char* a2 = last ? nA : cA + (size_t)(t + 2) * kstep; const char* b2 = last ? nB : cB + (size_t)(t + 2) * kstep;
;             const char* a3 = a2 + kstep; const char* b3 = b2 + kstep;
;     ...
; #pragma unroll
;         for (int a = 0; a < 2; ++a)
; #pragma unroll
;             for (int b = 0; b < 2; ++b)
; #pragma unroll
;                 for (int m = 0; m < 4; ++m)
; #pragma unroll
;                     for (int n = 0; n < 2; ++n) acc[a][b][m][n] = (f32x4){0.f, 0.f, 0.f, 0.f};
;         cur = nxt; cA = nA; cB = nB; ++ui;
.LBB0_1318:
	s_ashr_i32 s23, s22, 31
	s_lshl_b64 s[24:25], s[22:23], 18
	s_add_u32 s24, s58, s24
	s_addc_u32 s25, s59, s25
	s_and_b64 s[26:27], s[2:3], exec
	s_cselect_b32 s23, s25, s31
	s_cselect_b32 s53, s24, s30
	s_ashr_i32 s21, s20, 31
	s_lshl_b64 s[26:27], s[20:21], 18
	s_add_u32 s26, s76, s26
	s_addc_u32 s27, s77, s27
	s_and_b64 s[36:37], s[2:3], exec
	s_cselect_b32 s21, s27, s35
	s_cselect_b32 s62, s26, s34
	s_add_u32 s30, s30, 0x20080
	s_addc_u32 s31, s31, 0
	s_add_u32 s63, s34, 0x100
	v_mov_b32_e32 v0, 0
	s_addc_u32 s68, s35, 0
	s_mov_b32 s69, -2
	v_mov_b32_e32 v1, v0
	v_mov_b32_e32 v2, v0
	v_mov_b32_e32 v3, v0
	v_mov_b32_e32 v4, v0
	v_mov_b32_e32 v5, v0
	v_mov_b32_e32 v6, v0
	v_mov_b32_e32 v7, v0
	v_mov_b32_e32 v16, v0
	v_mov_b32_e32 v17, v0
	v_mov_b32_e32 v18, v0
	v_mov_b32_e32 v19, v0
	v_mov_b32_e32 v20, v0
	v_mov_b32_e32 v21, v0
	v_mov_b32_e32 v22, v0
	v_mov_b32_e32 v23, v0
	v_mov_b32_e32 v32, v0
	v_mov_b32_e32 v33, v0
	v_mov_b32_e32 v34, v0
	v_mov_b32_e32 v35, v0
	s_nop 0
	v_mov_b32_e32 v36, v0
	v_mov_b32_e32 v37, v0
	v_mov_b32_e32 v38, v0
	v_mov_b32_e32 v39, v0
	v_mov_b32_e32 v48, v0
	v_mov_b32_e32 v49, v0
	v_mov_b32_e32 v50, v0
	v_mov_b32_e32 v51, v0
	v_mov_b32_e32 v52, v0
	v_mov_b32_e32 v53, v0
	v_mov_b32_e32 v54, v0
	v_mov_b32_e32 v55, v0
	v_mov_b32_e32 v8, v0
	v_mov_b32_e32 v9, v0
	v_mov_b32_e32 v10, v0
	v_mov_b32_e32 v11, v0
	v_mov_b32_e32 v12, v0
	v_mov_b32_e32 v13, v0
	v_mov_b32_e32 v14, v0
	v_mov_b32_e32 v15, v0
	v_mov_b32_e32 v24, v0
	v_mov_b32_e32 v25, v0
	v_mov_b32_e32 v26, v0
	v_mov_b32_e32 v27, v0
	v_mov_b32_e32 v28, v0
	v_mov_b32_e32 v29, v0
	v_mov_b32_e32 v30, v0
	v_mov_b32_e32 v31, v0
	v_mov_b32_e32 v40, v0
	v_mov_b32_e32 v41, v0
	v_mov_b32_e32 v42, v0
	v_mov_b32_e32 v43, v0
	v_mov_b32_e32 v44, v0
	v_mov_b32_e32 v45, v0
	v_mov_b32_e32 v46, v0
	v_mov_b32_e32 v47, v0
	v_mov_b32_e32 v56, v0
	v_mov_b32_e32 v57, v0
	v_mov_b32_e32 v58, v0
	v_mov_b32_e32 v59, v0
	v_mov_b32_e32 v60, v0
	v_mov_b32_e32 v61, v0
	v_mov_b32_e32 v62, v0
	v_mov_b32_e32 v63, v0
	v_mov_b32_e32 v64, v0
	v_mov_b32_e32 v65, v0
	v_mov_b32_e32 v66, v0
	v_mov_b32_e32 v67, v0
	v_mov_b32_e32 v68, v0
	v_mov_b32_e32 v69, v0
	v_mov_b32_e32 v70, v0
	v_mov_b32_e32 v71, v0
	v_mov_b32_e32 v80, v0
	v_mov_b32_e32 v81, v0
	v_mov_b32_e32 v82, v0
	v_mov_b32_e32 v83, v0
	v_mov_b32_e32 v84, v0
	v_mov_b32_e32 v85, v0
	v_mov_b32_e32 v86, v0
	v_mov_b32_e32 v87, v0
	v_mov_b32_e32 v96, v0
	v_mov_b32_e32 v97, v0
	v_mov_b32_e32 v98, v0
	v_mov_b32_e32 v99, v0
	v_mov_b32_e32 v100, v0
	v_mov_b32_e32 v101, v0
	v_mov_b32_e32 v102, v0
	v_mov_b32_e32 v103, v0
	v_mov_b32_e32 v112, v0
	v_mov_b32_e32 v113, v0
	v_mov_b32_e32 v114, v0
	v_mov_b32_e32 v115, v0
	v_mov_b32_e32 v116, v0
	v_mov_b32_e32 v117, v0
	v_mov_b32_e32 v118, v0
	v_mov_b32_e32 v119, v0
	v_mov_b32_e32 v72, v0
	v_mov_b32_e32 v73, v0
	v_mov_b32_e32 v74, v0
	v_mov_b32_e32 v75, v0
	v_mov_b32_e32 v76, v0
	v_mov_b32_e32 v77, v0
	v_mov_b32_e32 v78, v0
	v_mov_b32_e32 v79, v0
	v_mov_b32_e32 v88, v0
	v_mov_b32_e32 v89, v0
	v_mov_b32_e32 v90, v0
	v_mov_b32_e32 v91, v0
	v_mov_b32_e32 v92, v0
	v_mov_b32_e32 v93, v0
	v_mov_b32_e32 v94, v0
	v_mov_b32_e32 v95, v0
	v_mov_b32_e32 v104, v0
	v_mov_b32_e32 v105, v0
	v_mov_b32_e32 v106, v0
	v_mov_b32_e32 v107, v0
	v_mov_b32_e32 v108, v0
	v_mov_b32_e32 v109, v0
	v_mov_b32_e32 v110, v0
	v_mov_b32_e32 v111, v0
	v_mov_b32_e32 v120, v0
	v_mov_b32_e32 v121, v0
	v_mov_b32_e32 v122, v0
	v_mov_b32_e32 v123, v0
	v_mov_b32_e32 v124, v0
	v_mov_b32_e32 v125, v0
	v_mov_b32_e32 v126, v0
	v_mov_b32_e32 v127, v0

; template <class Epi, class Sched, bool ALIGN_EPI = false, bool SP2 = false>
; __device__ __forceinline__ void gemm_phase(PG8_LAS unsigned char* lds, const Gemm g, const Sched& S, const Epi& E) {
;     ...
;     for (;;) {
;         const bool has_next = S.next(ui + 1, nxt);
;         const char* nA = has_next ? (const char*)g.A + (size_t)nxt.pm * tstep : cA; const char* nB = has_next ? (const char*)g.Bt + (size_t)nxt.pn * tstep : cB;
;         for (int t = 0; t < nt; t += 2) {
;             const bool last = (t == nt - 2);
;             const char* a1 = cA + (size_t)(t + 1) * kstep;
;             const char* a2 = last ? nA : cA + (size_t)(t + 2) * kstep; const char* b2 = last ? nB : cB + (size_t)(t + 2) * kstep;
;             const char* a3 = a2 + kstep; const char* b3 = b2 + kstep;
;     ...
; #pragma unroll
;         for (int a = 0; a < 2; ++a)
; #pragma unroll
;             for (int b = 0; b < 2; ++b)
; #pragma unroll
;                 for (int m = 0; m < 4; ++m)
; #pragma unroll
;                     for (int n = 0; n < 2; ++n) acc[a][b][m][n] = (f32x4){0.f, 0.f, 0.f, 0.f};
;         cur = nxt; cA = nA; cB = nB; ++ui;
.LBB0_1399:
	s_ashr_i32 s15, s14, 31
	s_lshl_b64 s[16:17], s[14:15], 19
	s_add_u32 s16, s54, s16
	s_addc_u32 s17, s55, s17
	s_and_b64 s[18:19], s[4:5], exec
	s_cselect_b32 s15, s17, s25
	s_cselect_b32 s21, s16, s24
	s_ashr_i32 s13, s12, 31
	s_lshl_b64 s[18:19], s[12:13], 19
	s_add_u32 s18, s74, s18
	s_addc_u32 s19, s75, s19
	s_and_b64 s[28:29], s[4:5], exec
	s_cselect_b32 s13, s19, s27
	s_cselect_b32 s57, s18, s26
	s_add_u32 s24, s24, 0x40080
	s_addc_u32 s25, s25, 0
	s_add_u32 s58, s26, 0x100
	v_mov_b32_e32 v0, 0
	s_addc_u32 s59, s27, 0
	s_mov_b32 s60, -2
	s_waitcnt lgkmcnt(0)
	v_mov_b32_e32 v1, v0
	v_mov_b32_e32 v2, v0
	v_mov_b32_e32 v3, v0
	v_mov_b32_e32 v4, v0
	v_mov_b32_e32 v5, v0
	v_mov_b32_e32 v6, v0
	v_mov_b32_e32 v7, v0
	v_mov_b32_e32 v16, v0
	v_mov_b32_e32 v17, v0
	v_mov_b32_e32 v18, v0
	v_mov_b32_e32 v19, v0
	v_mov_b32_e32 v20, v0
	v_mov_b32_e32 v21, v0
	v_mov_b32_e32 v22, v0
	v_mov_b32_e32 v23, v0
	v_mov_b32_e32 v32, v0
	v_mov_b32_e32 v33, v0
	v_mov_b32_e32 v34, v0
	v_mov_b32_e32 v35, v0
	s_nop 0
	v_mov_b32_e32 v36, v0
	v_mov_b32_e32 v37, v0
	v_mov_b32_e32 v38, v0
	v_mov_b32_e32 v39, v0
	v_mov_b32_e32 v48, v0
	v_mov_b32_e32 v49, v0
	v_mov_b32_e32 v50, v0
	v_mov_b32_e32 v51, v0
	v_mov_b32_e32 v52, v0
	v_mov_b32_e32 v53, v0
	v_mov_b32_e32 v54, v0
	v_mov_b32_e32 v55, v0
	v_mov_b32_e32 v8, v0
	v_mov_b32_e32 v9, v0
	v_mov_b32_e32 v10, v0
	v_mov_b32_e32 v11, v0
	v_mov_b32_e32 v12, v0
	v_mov_b32_e32 v13, v0
	v_mov_b32_e32 v14, v0
	v_mov_b32_e32 v15, v0
	v_mov_b32_e32 v24, v0
	v_mov_b32_e32 v25, v0
	v_mov_b32_e32 v26, v0
	v_mov_b32_e32 v27, v0
	v_mov_b32_e32 v28, v0
	v_mov_b32_e32 v29, v0
	v_mov_b32_e32 v30, v0
	v_mov_b32_e32 v31, v0
	v_mov_b32_e32 v40, v0
	v_mov_b32_e32 v41, v0
	v_mov_b32_e32 v42, v0
	v_mov_b32_e32 v43, v0
	v_mov_b32_e32 v44, v0
	v_mov_b32_e32 v45, v0
	v_mov_b32_e32 v46, v0
	v_mov_b32_e32 v47, v0
	v_mov_b32_e32 v56, v0
	v_mov_b32_e32 v57, v0
	v_mov_b32_e32 v58, v0
	v_mov_b32_e32 v59, v0
	v_mov_b32_e32 v60, v0
	v_mov_b32_e32 v61, v0
	v_mov_b32_e32 v62, v0
	v_mov_b32_e32 v63, v0
	v_mov_b32_e32 v64, v0
	v_mov_b32_e32 v65, v0
	v_mov_b32_e32 v66, v0
	v_mov_b32_e32 v67, v0
	v_mov_b32_e32 v68, v0
	v_mov_b32_e32 v69, v0
	v_mov_b32_e32 v70, v0
	v_mov_b32_e32 v71, v0
	v_mov_b32_e32 v80, v0
	v_mov_b32_e32 v81, v0
	v_mov_b32_e32 v82, v0
	v_mov_b32_e32 v83, v0
	v_mov_b32_e32 v84, v0
	v_mov_b32_e32 v85, v0
	v_mov_b32_e32 v86, v0
	v_mov_b32_e32 v87, v0
	v_mov_b32_e32 v96, v0
	v_mov_b32_e32 v97, v0
	v_mov_b32_e32 v98, v0
	v_mov_b32_e32 v99, v0
	v_mov_b32_e32 v100, v0
	v_mov_b32_e32 v101, v0
	v_mov_b32_e32 v102, v0
	v_mov_b32_e32 v103, v0
	v_mov_b32_e32 v112, v0
	v_mov_b32_e32 v113, v0
	v_mov_b32_e32 v114, v0
	v_mov_b32_e32 v115, v0
	v_mov_b32_e32 v116, v0
	v_mov_b32_e32 v117, v0
	v_mov_b32_e32 v118, v0
	v_mov_b32_e32 v119, v0
	v_mov_b32_e32 v72, v0
	v_mov_b32_e32 v73, v0
	v_mov_b32_e32 v74, v0
	v_mov_b32_e32 v75, v0
	v_mov_b32_e32 v76, v0
	v_mov_b32_e32 v77, v0
	v_mov_b32_e32 v78, v0
	v_mov_b32_e32 v79, v0
	v_mov_b32_e32 v88, v0
	v_mov_b32_e32 v89, v0
	v_mov_b32_e32 v90, v0
	v_mov_b32_e32 v91, v0
	v_mov_b32_e32 v92, v0
	v_mov_b32_e32 v93, v0
	v_mov_b32_e32 v94, v0
	v_mov_b32_e32 v95, v0
	v_mov_b32_e32 v104, v0
	v_mov_b32_e32 v105, v0
	v_mov_b32_e32 v106, v0
	v_mov_b32_e32 v107, v0
	v_mov_b32_e32 v108, v0
	v_mov_b32_e32 v109, v0
	v_mov_b32_e32 v110, v0
	v_mov_b32_e32 v111, v0
	v_mov_b32_e32 v120, v0
	v_mov_b32_e32 v121, v0
	v_mov_b32_e32 v122, v0
	v_mov_b32_e32 v123, v0
	v_mov_b32_e32 v124, v0
	v_mov_b32_e32 v125, v0
	v_mov_b32_e32 v126, v0
	v_mov_b32_e32 v127, v0

; template <class Epi, class Sched, bool ALIGN_EPI = false, bool SP2 = false>
; __device__ __forceinline__ void gemm_phase(PG8_LAS unsigned char* lds, const Gemm g, const Sched& S, const Epi& E) {
;     ...
;     for (;;) {
;         const bool has_next = S.next(ui + 1, nxt);
;         const char* nA = has_next ? (const char*)g.A + (size_t)nxt.pm * tstep : cA; const char* nB = has_next ? (const char*)g.Bt + (size_t)nxt.pn * tstep : cB;
;         for (int t = 0; t < nt; t += 2) {
;             const bool last = (t == nt - 2);
;             const char* a1 = cA + (size_t)(t + 1) * kstep;
;             const char* a2 = last ? nA : cA + (size_t)(t + 2) * kstep; const char* b2 = last ? nB : cB + (size_t)(t + 2) * kstep;
;             const char* a3 = a2 + kstep; const char* b3 = b2 + kstep;
;     ...
; #pragma unroll
;         for (int a = 0; a < 2; ++a)
; #pragma unroll
;             for (int b = 0; b < 2; ++b)
; #pragma unroll
;                 for (int m = 0; m < 4; ++m)
; #pragma unroll
;                     for (int n = 0; n < 2; ++n) acc[a][b][m][n] = (f32x4){0.f, 0.f, 0.f, 0.f};
;         cur = nxt; cA = nA; cB = nB; ++ui;
.LBB0_1486:
	s_ashr_i32 s23, s22, 31
	s_lshl_b64 s[8:9], s[22:23], 19
	s_add_u32 s24, s92, s8
	s_addc_u32 s25, s93, s9
	s_and_b64 s[8:9], s[2:3], exec
	s_cselect_b32 s10, s25, s5
	s_cselect_b32 s11, s24, s4
	s_ashr_i32 s21, s20, 31
	s_lshl_b64 s[8:9], s[20:21], 19
	s_add_u32 s26, s90, s8
	s_addc_u32 s27, s91, s9
	s_and_b64 s[8:9], s[2:3], exec
	s_cselect_b32 s21, s27, s7
	s_cselect_b32 s23, s26, s6
	s_add_u32 s4, s4, 0x40080
	s_addc_u32 s5, s5, 0
	s_add_u32 s45, s6, 0x100
	v_mov_b32_e32 v0, 0
	s_addc_u32 s50, s7, 0
	s_mov_b32 s51, -2
	v_mov_b32_e32 v1, v0
	v_mov_b32_e32 v2, v0
	v_mov_b32_e32 v3, v0
	v_mov_b32_e32 v8, v0
	v_mov_b32_e32 v9, v0
	v_mov_b32_e32 v10, v0
	v_mov_b32_e32 v11, v0
	v_mov_b32_e32 v16, v0
	v_mov_b32_e32 v17, v0
	v_mov_b32_e32 v18, v0
	v_mov_b32_e32 v19, v0
	v_mov_b32_e32 v24, v0
	v_mov_b32_e32 v25, v0
	v_mov_b32_e32 v26, v0
	v_mov_b32_e32 v27, v0
	v_mov_b32_e32 v32, v0
	v_mov_b32_e32 v33, v0
	v_mov_b32_e32 v34, v0
	v_mov_b32_e32 v35, v0
	s_nop 0
	v_mov_b32_e32 v40, v0
	v_mov_b32_e32 v41, v0
	v_mov_b32_e32 v42, v0
	v_mov_b32_e32 v43, v0
	v_mov_b32_e32 v48, v0
	v_mov_b32_e32 v49, v0
	v_mov_b32_e32 v50, v0
	v_mov_b32_e32 v51, v0
	v_mov_b32_e32 v56, v0
	v_mov_b32_e32 v57, v0
	v_mov_b32_e32 v58, v0
	v_mov_b32_e32 v59, v0
	v_mov_b32_e32 v4, v0
	v_mov_b32_e32 v5, v0
	v_mov_b32_e32 v6, v0
	v_mov_b32_e32 v7, v0
	v_mov_b32_e32 v12, v0
	v_mov_b32_e32 v13, v0
	v_mov_b32_e32 v14, v0
	v_mov_b32_e32 v15, v0
	v_mov_b32_e32 v20, v0
	v_mov_b32_e32 v21, v0
	v_mov_b32_e32 v22, v0
	v_mov_b32_e32 v23, v0
	v_mov_b32_e32 v28, v0
	v_mov_b32_e32 v29, v0
	v_mov_b32_e32 v30, v0
	v_mov_b32_e32 v31, v0
	v_mov_b32_e32 v36, v0
	v_mov_b32_e32 v37, v0
	v_mov_b32_e32 v38, v0
	v_mov_b32_e32 v39, v0
	v_mov_b32_e32 v44, v0
	v_mov_b32_e32 v45, v0
	v_mov_b32_e32 v46, v0
	v_mov_b32_e32 v47, v0
	v_mov_b32_e32 v52, v0
	v_mov_b32_e32 v53, v0
	v_mov_b32_e32 v54, v0
	v_mov_b32_e32 v55, v0
	v_mov_b32_e32 v60, v0
	v_mov_b32_e32 v61, v0
	v_mov_b32_e32 v62, v0
	v_mov_b32_e32 v63, v0
	v_mov_b32_e32 v64, v0
	v_mov_b32_e32 v65, v0
	v_mov_b32_e32 v66, v0
	v_mov_b32_e32 v67, v0
	v_mov_b32_e32 v72, v0
	v_mov_b32_e32 v73, v0
	v_mov_b32_e32 v74, v0
	v_mov_b32_e32 v75, v0
	v_mov_b32_e32 v80, v0
	v_mov_b32_e32 v81, v0
	v_mov_b32_e32 v82, v0
	v_mov_b32_e32 v83, v0
	v_mov_b32_e32 v88, v0
	v_mov_b32_e32 v89, v0
	v_mov_b32_e32 v90, v0
	v_mov_b32_e32 v91, v0
	v_mov_b32_e32 v96, v0
	v_mov_b32_e32 v97, v0
	v_mov_b32_e32 v98, v0
	v_mov_b32_e32 v99, v0
	v_mov_b32_e32 v104, v0
	v_mov_b32_e32 v105, v0
	v_mov_b32_e32 v106, v0
	v_mov_b32_e32 v107, v0
	v_mov_b32_e32 v112, v0
	v_mov_b32_e32 v113, v0
	v_mov_b32_e32 v114, v0
	v_mov_b32_e32 v115, v0
	v_mov_b32_e32 v120, v0
	v_mov_b32_e32 v121, v0
	v_mov_b32_e32 v122, v0
	v_mov_b32_e32 v123, v0
	v_mov_b32_e32 v68, v0
	v_mov_b32_e32 v69, v0
	v_mov_b32_e32 v70, v0
	v_mov_b32_e32 v71, v0
	v_mov_b32_e32 v76, v0
	v_mov_b32_e32 v77, v0
	v_mov_b32_e32 v78, v0
	v_mov_b32_e32 v79, v0
	v_mov_b32_e32 v84, v0
	v_mov_b32_e32 v85, v0
	v_mov_b32_e32 v86, v0
	v_mov_b32_e32 v87, v0
	v_mov_b32_e32 v92, v0
	v_mov_b32_e32 v93, v0
	v_mov_b32_e32 v94, v0
	v_mov_b32_e32 v95, v0
	v_mov_b32_e32 v100, v0
	v_mov_b32_e32 v101, v0
	v_mov_b32_e32 v102, v0
	v_mov_b32_e32 v103, v0
	v_mov_b32_e32 v108, v0
	v_mov_b32_e32 v109, v0
	v_mov_b32_e32 v110, v0
	v_mov_b32_e32 v111, v0
	v_mov_b32_e32 v116, v0
	v_mov_b32_e32 v117, v0
	v_mov_b32_e32 v118, v0
	v_mov_b32_e32 v119, v0
	v_mov_b32_e32 v124, v0
	v_mov_b32_e32 v125, v0
	v_mov_b32_e32 v126, v0
	v_mov_b32_e32 v127, v0

; template <class Epi, class Sched, bool ALIGN_EPI = false, bool SP2 = false>
; __device__ __forceinline__ void gemm_phase(PG8_LAS unsigned char* lds, const Gemm g, const Sched& S, const Epi& E) {
;     ...
;     for (;;) {
;         const bool has_next = S.next(ui + 1, nxt);
;         const char* nA = has_next ? (const char*)g.A + (size_t)nxt.pm * tstep : cA; const char* nB = has_next ? (const char*)g.Bt + (size_t)nxt.pn * tstep : cB;
;         for (int t = 0; t < nt; t += 2) {
;             const bool last = (t == nt - 2);
;             const char* a1 = cA + (size_t)(t + 1) * kstep;
;             const char* a2 = last ? nA : cA + (size_t)(t + 2) * kstep; const char* b2 = last ? nB : cB + (size_t)(t + 2) * kstep;
;             const char* a3 = a2 + kstep; const char* b3 = b2 + kstep;
;     ...
; #pragma unroll
;         for (int a = 0; a < 2; ++a)
; #pragma unroll
;             for (int b = 0; b < 2; ++b)
; #pragma unroll
;                 for (int m = 0; m < 4; ++m)
; #pragma unroll
;                     for (int n = 0; n < 2; ++n) acc[a][b][m][n] = (f32x4){0.f, 0.f, 0.f, 0.f};
;         cur = nxt; cA = nA; cB = nB; ++ui;
.LBB0_1571:
	s_add_u32 s20, s20, 0xb0080
	s_addc_u32 s21, s21, 0
	s_add_u32 s45, s22, 0x100
	v_mov_b32_e32 v0, 0
	s_addc_u32 s46, s23, 0
	s_mov_b32 s47, -2
	v_mov_b32_e32 v1, v0
	v_mov_b32_e32 v2, v0
	v_mov_b32_e32 v3, v0
	v_mov_b32_e32 v4, v0
	v_mov_b32_e32 v5, v0
	v_mov_b32_e32 v6, v0
	v_mov_b32_e32 v7, v0
	v_mov_b32_e32 v16, v0
	v_mov_b32_e32 v17, v0
	v_mov_b32_e32 v18, v0
	v_mov_b32_e32 v19, v0
	v_mov_b32_e32 v20, v0
	v_mov_b32_e32 v21, v0
	v_mov_b32_e32 v22, v0
	v_mov_b32_e32 v23, v0
	v_mov_b32_e32 v32, v0
	v_mov_b32_e32 v33, v0
	v_mov_b32_e32 v34, v0
	v_mov_b32_e32 v35, v0
	s_nop 0
	v_mov_b32_e32 v36, v0
	v_mov_b32_e32 v37, v0
	v_mov_b32_e32 v38, v0
	v_mov_b32_e32 v39, v0
	v_mov_b32_e32 v48, v0
	v_mov_b32_e32 v49, v0
	v_mov_b32_e32 v50, v0
	v_mov_b32_e32 v51, v0
	v_mov_b32_e32 v52, v0
	v_mov_b32_e32 v53, v0
	v_mov_b32_e32 v54, v0
	v_mov_b32_e32 v55, v0
	v_mov_b32_e32 v8, v0
	v_mov_b32_e32 v9, v0
	v_mov_b32_e32 v10, v0
	v_mov_b32_e32 v11, v0
	v_mov_b32_e32 v12, v0
	v_mov_b32_e32 v13, v0
	v_mov_b32_e32 v14, v0
	v_mov_b32_e32 v15, v0
	v_mov_b32_e32 v24, v0
	v_mov_b32_e32 v25, v0
	v_mov_b32_e32 v26, v0
	v_mov_b32_e32 v27, v0
	v_mov_b32_e32 v28, v0
	v_mov_b32_e32 v29, v0
	v_mov_b32_e32 v30, v0
	v_mov_b32_e32 v31, v0
	v_mov_b32_e32 v40, v0
	v_mov_b32_e32 v41, v0
	v_mov_b32_e32 v42, v0
	v_mov_b32_e32 v43, v0
	v_mov_b32_e32 v44, v0
	v_mov_b32_e32 v45, v0
	v_mov_b32_e32 v46, v0
	v_mov_b32_e32 v47, v0
	v_mov_b32_e32 v56, v0
	v_mov_b32_e32 v57, v0
	v_mov_b32_e32 v58, v0
	v_mov_b32_e32 v59, v0
	v_mov_b32_e32 v60, v0
	v_mov_b32_e32 v61, v0
	v_mov_b32_e32 v62, v0
	v_mov_b32_e32 v63, v0
	v_mov_b32_e32 v64, v0
	v_mov_b32_e32 v65, v0
	v_mov_b32_e32 v66, v0
	v_mov_b32_e32 v67, v0
	v_mov_b32_e32 v68, v0
	v_mov_b32_e32 v69, v0
	v_mov_b32_e32 v70, v0
	v_mov_b32_e32 v71, v0
	v_mov_b32_e32 v80, v0
	v_mov_b32_e32 v81, v0
	v_mov_b32_e32 v82, v0
	v_mov_b32_e32 v83, v0
	v_mov_b32_e32 v84, v0
	v_mov_b32_e32 v85, v0
	v_mov_b32_e32 v86, v0
	v_mov_b32_e32 v87, v0
	v_mov_b32_e32 v96, v0
	v_mov_b32_e32 v97, v0
	v_mov_b32_e32 v98, v0
	v_mov_b32_e32 v99, v0
	v_mov_b32_e32 v100, v0
	v_mov_b32_e32 v101, v0
	v_mov_b32_e32 v102, v0
	v_mov_b32_e32 v103, v0
	v_mov_b32_e32 v112, v0
	v_mov_b32_e32 v113, v0
	v_mov_b32_e32 v114, v0
	v_mov_b32_e32 v115, v0
	v_mov_b32_e32 v116, v0
	v_mov_b32_e32 v117, v0
	v_mov_b32_e32 v118, v0
	v_mov_b32_e32 v119, v0
	v_mov_b32_e32 v72, v0
	v_mov_b32_e32 v73, v0
	v_mov_b32_e32 v74, v0
	v_mov_b32_e32 v75, v0
	v_mov_b32_e32 v76, v0
	v_mov_b32_e32 v77, v0
	v_mov_b32_e32 v78, v0
	v_mov_b32_e32 v79, v0
	v_mov_b32_e32 v88, v0
	v_mov_b32_e32 v89, v0
	v_mov_b32_e32 v90, v0
	v_mov_b32_e32 v91, v0
	v_mov_b32_e32 v92, v0
	v_mov_b32_e32 v93, v0
	v_mov_b32_e32 v94, v0
	v_mov_b32_e32 v95, v0
	v_mov_b32_e32 v104, v0
	v_mov_b32_e32 v105, v0
	v_mov_b32_e32 v106, v0
	v_mov_b32_e32 v107, v0
	v_mov_b32_e32 v108, v0
	v_mov_b32_e32 v109, v0
	v_mov_b32_e32 v110, v0
	v_mov_b32_e32 v111, v0
	v_mov_b32_e32 v120, v0
	v_mov_b32_e32 v121, v0
	v_mov_b32_e32 v122, v0
	v_mov_b32_e32 v123, v0
	v_mov_b32_e32 v124, v0
	v_mov_b32_e32 v125, v0
	v_mov_b32_e32 v126, v0
	v_mov_b32_e32 v127, v0

; template <class Epi, class Sched, bool ALIGN_EPI = false, bool SP2 = false>
; __device__ __forceinline__ void gemm_phase(PG8_LAS unsigned char* lds, const Gemm g, const Sched& S, const Epi& E) {
;     ...
;     for (;;) {
;         const bool has_next = S.next(ui + 1, nxt);
;         const char* nA = has_next ? (const char*)g.A + (size_t)nxt.pm * tstep : cA; const char* nB = has_next ? (const char*)g.Bt + (size_t)nxt.pn * tstep : cB;
;         for (int t = 0; t < nt; t += 2) {
;             const bool last = (t == nt - 2);
;             const char* a1 = cA + (size_t)(t + 1) * kstep;
;             const char* a2 = last ? nA : cA + (size_t)(t + 2) * kstep; const char* b2 = last ? nB : cB + (size_t)(t + 2) * kstep;
;             const char* a3 = a2 + kstep; const char* b3 = b2 + kstep;
;     ...
; #pragma unroll
;         for (int a = 0; a < 2; ++a)
; #pragma unroll
;             for (int b = 0; b < 2; ++b)
; #pragma unroll
;                 for (int m = 0; m < 4; ++m)
; #pragma unroll
;                     for (int n = 0; n < 2; ++n) acc[a][b][m][n] = (f32x4){0.f, 0.f, 0.f, 0.f};
;         cur = nxt; cA = nA; cB = nB; ++ui;
.LBB0_1665:
	s_ashr_i32 s27, s26, 31
	s_lshl_b64 s[8:9], s[26:27], 19
	s_add_u32 s28, s34, s8
	s_addc_u32 s29, s35, s9
	s_and_b64 s[8:9], s[2:3], exec
	s_cselect_b32 s10, s29, s5
	s_cselect_b32 s11, s28, s4
	s_ashr_i32 s25, s24, 31
	s_lshl_b64 s[8:9], s[24:25], 19
	s_add_u32 s30, s90, s8
	s_addc_u32 s31, s91, s9
	s_and_b64 s[8:9], s[2:3], exec
	s_cselect_b32 s25, s31, s7
	s_cselect_b32 s27, s30, s6
	s_add_u32 s4, s4, 0x40080
	s_addc_u32 s5, s5, 0
	s_add_u32 s53, s6, 0x100
	v_mov_b32_e32 v0, 0
	s_addc_u32 s54, s7, 0
	s_mov_b32 s55, -2
	v_mov_b32_e32 v1, v0
	v_mov_b32_e32 v2, v0
	v_mov_b32_e32 v3, v0
	v_mov_b32_e32 v8, v0
	v_mov_b32_e32 v9, v0
	v_mov_b32_e32 v10, v0
	v_mov_b32_e32 v11, v0
	v_mov_b32_e32 v16, v0
	v_mov_b32_e32 v17, v0
	v_mov_b32_e32 v18, v0
	v_mov_b32_e32 v19, v0
	v_mov_b32_e32 v24, v0
	v_mov_b32_e32 v25, v0
	v_mov_b32_e32 v26, v0
	v_mov_b32_e32 v27, v0
	v_mov_b32_e32 v32, v0
	v_mov_b32_e32 v33, v0
	v_mov_b32_e32 v34, v0
	v_mov_b32_e32 v35, v0
	s_nop 0
	v_mov_b32_e32 v40, v0
	v_mov_b32_e32 v41, v0
	v_mov_b32_e32 v42, v0
	v_mov_b32_e32 v43, v0
	v_mov_b32_e32 v48, v0
	v_mov_b32_e32 v49, v0
	v_mov_b32_e32 v50, v0
	v_mov_b32_e32 v51, v0
	v_mov_b32_e32 v56, v0
	v_mov_b32_e32 v57, v0
	v_mov_b32_e32 v58, v0
	v_mov_b32_e32 v59, v0
	v_mov_b32_e32 v4, v0
	v_mov_b32_e32 v5, v0
	v_mov_b32_e32 v6, v0
	v_mov_b32_e32 v7, v0
	v_mov_b32_e32 v12, v0
	v_mov_b32_e32 v13, v0
	v_mov_b32_e32 v14, v0
	v_mov_b32_e32 v15, v0
	v_mov_b32_e32 v20, v0
	v_mov_b32_e32 v21, v0
	v_mov_b32_e32 v22, v0
	v_mov_b32_e32 v23, v0
	v_mov_b32_e32 v28, v0
	v_mov_b32_e32 v29, v0
	v_mov_b32_e32 v30, v0
	v_mov_b32_e32 v31, v0
	v_mov_b32_e32 v36, v0
	v_mov_b32_e32 v37, v0
	v_mov_b32_e32 v38, v0
	v_mov_b32_e32 v39, v0
	v_mov_b32_e32 v44, v0
	v_mov_b32_e32 v45, v0
	v_mov_b32_e32 v46, v0
	v_mov_b32_e32 v47, v0
	v_mov_b32_e32 v52, v0
	v_mov_b32_e32 v53, v0
	v_mov_b32_e32 v54, v0
	v_mov_b32_e32 v55, v0
	v_mov_b32_e32 v60, v0
	v_mov_b32_e32 v61, v0
	v_mov_b32_e32 v62, v0
	v_mov_b32_e32 v63, v0
	v_mov_b32_e32 v64, v0
	v_mov_b32_e32 v65, v0
	v_mov_b32_e32 v66, v0
	v_mov_b32_e32 v67, v0
	v_mov_b32_e32 v72, v0
	v_mov_b32_e32 v73, v0
	v_mov_b32_e32 v74, v0
	v_mov_b32_e32 v75, v0
	v_mov_b32_e32 v80, v0
	v_mov_b32_e32 v81, v0
	v_mov_b32_e32 v82, v0
	v_mov_b32_e32 v83, v0
	v_mov_b32_e32 v88, v0
	v_mov_b32_e32 v89, v0
	v_mov_b32_e32 v90, v0
	v_mov_b32_e32 v91, v0
	v_mov_b32_e32 v96, v0
	v_mov_b32_e32 v97, v0
	v_mov_b32_e32 v98, v0
	v_mov_b32_e32 v99, v0
	v_mov_b32_e32 v104, v0
	v_mov_b32_e32 v105, v0
	v_mov_b32_e32 v106, v0
	v_mov_b32_e32 v107, v0
	v_mov_b32_e32 v112, v0
	v_mov_b32_e32 v113, v0
	v_mov_b32_e32 v114, v0
	v_mov_b32_e32 v115, v0
	v_mov_b32_e32 v120, v0
	v_mov_b32_e32 v121, v0
	v_mov_b32_e32 v122, v0
	v_mov_b32_e32 v123, v0
	v_mov_b32_e32 v68, v0
	v_mov_b32_e32 v69, v0
	v_mov_b32_e32 v70, v0
	v_mov_b32_e32 v71, v0
	v_mov_b32_e32 v76, v0
	v_mov_b32_e32 v77, v0
	v_mov_b32_e32 v78, v0
	v_mov_b32_e32 v79, v0
	v_mov_b32_e32 v84, v0
	v_mov_b32_e32 v85, v0
	v_mov_b32_e32 v86, v0
	v_mov_b32_e32 v87, v0
	v_mov_b32_e32 v92, v0
	v_mov_b32_e32 v93, v0
	v_mov_b32_e32 v94, v0
	v_mov_b32_e32 v95, v0
	v_mov_b32_e32 v100, v0
	v_mov_b32_e32 v101, v0
	v_mov_b32_e32 v102, v0
	v_mov_b32_e32 v103, v0
	v_mov_b32_e32 v108, v0
	v_mov_b32_e32 v109, v0
	v_mov_b32_e32 v110, v0
	v_mov_b32_e32 v111, v0
	v_mov_b32_e32 v116, v0
	v_mov_b32_e32 v117, v0
	v_mov_b32_e32 v118, v0
	v_mov_b32_e32 v119, v0
	v_mov_b32_e32 v124, v0
	v_mov_b32_e32 v125, v0
	v_mov_b32_e32 v126, v0
	v_mov_b32_e32 v127, v0
